# static s_setprio 1 for waves 0-3 of each workgroup for the whole kernel (on top of v28)
# speedup vs baseline: 1.0380x; 1.0086x over previous
; __device__ __forceinline__ int vblk() { return (int)blockIdx.x * 2 + half_id(); }
; __device__ __forceinline__ int vgrid() { return (int)gridDim.x * 2; }
; __device__ void phaseA(const Params& p, char* lds) {
;     const int tid = TIDX;
;     float* fl = (float*)lds;
;     constexpr int N0 = TA_E1 + (TA_E8 - TA_E6) + (TA_E11 - TA_E10);
;     float pre[16];
;     bool pre_valid = false;
;     for (int idx = vblk(); idx < N0; idx += vgrid()) {
;         const int task = idx < TA_E1 ? idx : (idx < TA_E1 + (TA_E8 - TA_E6) ? idx - TA_E1 + TA_E6 : idx - TA_E1 - (TA_E8 - TA_E6) + TA_E10);
;     ...
;             const int tt = task - TA_E10;
;             const int e = tt * 256 + tid;
;             const int tok = e >> 3, i = e & 7;
;             const float invf[8] = {1.0f, 0.1939227432012558f, 0.03760603070259094f, 0.007292664609849453f,
;                                    0.0014142135623842478f, 0.00027424818836152554f, 5.318296098266728e-05f, 1.0313386155758053e-05f};
;             float fr = invf[0];
; #pragma unroll
;             for (int j = 1; j < 8; j++) fr = (i == j) ? invf[j] : fr;
;             const float ang = (float)p.pos[tok] * fr;
;             const double rev = (double)ang * 0.15915494309189533577;
;             const float fpart = (float)(rev - floor(rev));
.LBB0_6:
	s_or_b64 exec, exec, s[4:5]
	v_readfirstlane_b32 s0, v158
	v_readlane_b32 s1, v222, 0
	s_lshr_b32 s0, s0, 8
	s_lshl_b32 s85, s1, 1
	s_mul_i32 s33, s0, 0x12000
	s_cmp_eq_u32 s33, 0
	s_cbranch_scc0 .Lprio_all_skip
	s_setprio 1
.Lprio_all_skip:
	s_add_i32 s0, s0, s85
	s_mov_b64 s[6:7], s[80:81]
	v_mov_b32_e32 v2, v158
	s_cmpk_gt_i32 s0, 0x7df
	s_cbranch_scc1 .LBB0_171
	s_add_u32 s8, s6, 0x80
	s_addc_u32 s9, s7, 0
	s_add_u32 s10, s6, 0x70
	s_addc_u32 s11, s7, 0
	s_add_u32 s14, s6, 64
	v_and_b32_e32 v120, 31, v2
	v_bfe_u32 v7, v2, 5, 3
	v_and_b32_e32 v5, 7, v2
	s_addc_u32 s15, s7, 0
	v_lshlrev_b32_e32 v9, 10, v7
	v_lshlrev_b32_e32 v11, 2, v120
	s_add_u32 s16, s6, 0xa8
	v_add3_u32 v125, s33, v9, v11
	v_mov_b32_e32 v9, 0x3e4693af
	v_cmp_eq_u32_e32 vcc, 1, v5
	s_addc_u32 s17, s7, 0
	v_mov_b32_e32 v11, 0x3d1a08c8
	v_cndmask_b32_e32 v9, 1.0, v9, vcc
	v_cmp_ne_u32_e32 vcc, 2, v5
	s_add_u32 s18, s6, 0xa0
	s_addc_u32 s19, s7, 0
	v_cndmask_b32_e32 v9, v11, v9, vcc
	v_mov_b32_e32 v11, 0x3beef74e
	v_cmp_ne_u32_e32 vcc, 3, v5
	v_and_b32_e32 v3, 0xff, v2
	s_add_u32 s20, s6, 0x98
	v_cndmask_b32_e32 v9, v11, v9, vcc
	v_mov_b32_e32 v11, 0x3ab95d22
	v_cmp_ne_u32_e32 vcc, 4, v5
	v_lshlrev_b32_e32 v4, 2, v3
	v_mul_u32_u24_e32 v2, 0x1800, v7
	v_cndmask_b32_e32 v9, v11, v9, vcc
	v_mov_b32_e32 v11, 0x398fc8f8
	v_cmp_ne_u32_e32 vcc, 5, v5
	s_addc_u32 s21, s7, 0
	v_or_b32_e32 v1, 0xfff2a000, v3
	v_cndmask_b32_e32 v9, v11, v9, vcc
	v_mov_b32_e32 v11, 0x385f10c5
	v_cmp_ne_u32_e32 vcc, 6, v5
	v_lshlrev_b32_e32 v121, 7, v7
	v_or_b32_e32 v123, v2, v120
	s_add_u32 s22, s6, 0x90
	v_or_b32_e32 v2, 0x400, v4
	v_or_b32_e32 v6, 0x800, v4
	v_or_b32_e32 v8, 0xc00, v4
	v_or_b32_e32 v10, 0x1000, v4
	v_or_b32_e32 v12, 0x1400, v4
	v_or_b32_e32 v14, 0x1800, v4
	v_or_b32_e32 v16, 0x1c00, v4
	v_lshl_add_u32 v124, v3, 4, s33
	v_mul_i32_i24_e32 v3, -12, v3
	v_cndmask_b32_e32 v9, v11, v9, vcc
	v_mov_b32_e32 v11, 0x372d07a8
	v_cmp_ne_u32_e32 vcc, 7, v5
	v_mul_u32_u24_e32 v5, 0x300000, v7
	s_mov_b32 s24, 0x6dc9c883
	v_add_u32_e32 v122, 0x80, v121
	s_addc_u32 s23, s7, 0
	v_mov_b32_e32 v103, 0
	v_cndmask_b32_e32 v126, v11, v9, vcc
	v_lshl_add_u32 v127, v7, 9, s33
	v_mul_hi_u32_u24_e32 v105, 0x300000, v7
	v_or_b32_e32 v104, 0x5a000, v5
	s_mov_b64 s[38:39], 0
	s_mov_b32 s25, 0x3fc45f30
	s_mov_b32 s27, 0
	s_movk_i32 s1, 0xfc
	s_mov_b64 s[28:29], 0x2f4000
	s_mov_b64 s[30:31], 0x2b4000
	s_movk_i32 s2, 0x132f
	s_movk_i32 s3, 0x1340
	s_movk_i32 s54, 0x1b40
	s_mov_b64 s[34:35], 0x400000
	v_lshlrev_b32_e32 v128, 2, v4
	v_lshlrev_b32_e32 v129, 2, v2
	v_lshlrev_b32_e32 v130, 2, v6
	v_lshlrev_b32_e32 v131, 2, v8
	v_lshlrev_b32_e32 v132, 2, v10
	v_lshlrev_b32_e32 v133, 2, v12
	v_lshlrev_b32_e32 v134, 2, v14
	v_lshlrev_b32_e32 v135, 2, v16
	s_mov_b32 s55, 0xfffa6000
	s_mov_b32 s56, 0xfffac000
	s_mov_b32 s57, 0xfffb2000
	s_mov_b32 s58, 0xfffb8000
	s_mov_b32 s59, 0xfffbe000
	s_mov_b32 s60, 0xfffc4000
	s_mov_b32 s61, 0xfffca000
	s_mov_b32 s62, 0xfffd0000
	s_mov_b32 s63, 0xfffd6000
	s_mov_b32 s64, 0xfffdc000
	s_mov_b32 s65, 0xfffe2000
	s_mov_b32 s66, 0xfffe8000
	s_mov_b32 s67, 0xfffee000
	s_mov_b32 s68, 0xffff4000
	s_movk_i32 s69, 0xa000
	s_mov_b64 s[36:37], 0x60000
	v_add_u32_e32 v136, v124, v3
	s_movk_i32 s70, 0xbff
	v_mov_b32_e32 v137, 2
	s_branch .LBB0_11
